# CONV6: conv output groups 1-7 computed stage by stage (7 tile reads together, FMA chains into separate registers, SiLU as 14-wide stages) instead of read-wait-chain per group; on top of DPP+CONV5
# baseline (speedup 1.0000x reference)
; __device__ __forceinline__ void phase_conv(const Params& p, LAS unsigned char* lds, int wg, int G, int tid) {
;     ...
;         f32x2 v0 = tp[(ib0 + 0) * 32], v1 = tp[(ib0 + 1) * 32], v2 = tp[(ib0 + 2) * 32];
; #pragma unroll
;         for (int k = 0; k < 8; ++k) {
;             const f32x2 v3 = tp[(ib0 + k + 3) * 32];
;             f32x2 a = bias + w0 * v0 + w1 * v1 + w2 * v2 + w3 * v3;
;             if (act) { f32x2 d; d.x = 1.f + __expf(-a.x); d.y = 1.f + __expf(-a.y); f32x2 rc; rc.x = __builtin_amdgcn_rcpf(d.x); rc.y = __builtin_amdgcn_rcpf(d.y); a = a * rc; }
;             o[k] = a;
;             v0 = v1; v1 = v2; v2 = v3;
;         }
.LBB0_652:
	ds_read_b64 v[28:29], v27 offset:1024
	ds_read_b64 v[40:41], v27 offset:1280
	ds_read_b64 v[42:43], v27 offset:1536
	ds_read_b64 v[44:45], v27 offset:1792
	ds_read_b64 v[46:47], v27 offset:2048
	ds_read_b64 v[48:49], v27 offset:2304
	ds_read_b64 v[64:65], v27 offset:2560
	v_pk_fma_f32 v[100:101], v[30:31], v[18:19], v[32:33]
	v_pk_fma_f32 v[102:103], v[30:31], v[12:13], v[32:33]
	v_pk_fma_f32 v[104:105], v[30:31], v[14:15], v[32:33]
	s_waitcnt lgkmcnt(0)
	v_pk_fma_f32 v[106:107], v[30:31], v[28:29], v[32:33]
	v_pk_fma_f32 v[108:109], v[30:31], v[40:41], v[32:33]
	v_pk_fma_f32 v[110:111], v[30:31], v[42:43], v[32:33]
	v_pk_fma_f32 v[112:113], v[30:31], v[44:45], v[32:33]
	v_pk_fma_f32 v[100:101], v[38:39], v[12:13], v[100:101]
	v_pk_fma_f32 v[102:103], v[38:39], v[14:15], v[102:103]
	v_pk_fma_f32 v[104:105], v[38:39], v[28:29], v[104:105]
	v_pk_fma_f32 v[106:107], v[38:39], v[40:41], v[106:107]
	v_pk_fma_f32 v[108:109], v[38:39], v[42:43], v[108:109]
	v_pk_fma_f32 v[110:111], v[38:39], v[44:45], v[110:111]
	v_pk_fma_f32 v[112:113], v[38:39], v[46:47], v[112:113]
	v_pk_fma_f32 v[100:101], v[36:37], v[14:15], v[100:101]
	v_pk_fma_f32 v[102:103], v[36:37], v[28:29], v[102:103]
	v_pk_fma_f32 v[104:105], v[36:37], v[40:41], v[104:105]
	v_pk_fma_f32 v[106:107], v[36:37], v[42:43], v[106:107]
	v_pk_fma_f32 v[108:109], v[36:37], v[44:45], v[108:109]
	v_pk_fma_f32 v[110:111], v[36:37], v[46:47], v[110:111]
	v_pk_fma_f32 v[112:113], v[36:37], v[48:49], v[112:113]
	v_pk_fma_f32 v[100:101], v[34:35], v[28:29], v[100:101]
	v_pk_fma_f32 v[102:103], v[34:35], v[40:41], v[102:103]
	v_pk_fma_f32 v[104:105], v[34:35], v[42:43], v[104:105]
	v_pk_fma_f32 v[106:107], v[34:35], v[44:45], v[106:107]
	v_pk_fma_f32 v[108:109], v[34:35], v[46:47], v[108:109]
	v_pk_fma_f32 v[110:111], v[34:35], v[48:49], v[110:111]
	v_pk_fma_f32 v[112:113], v[34:35], v[64:65], v[112:113]
	s_andn2_b64 vcc, exec, s[50:51]
	s_cbranch_vccnz .Lconv_nosilu
	v_mul_f32_e32 v114, 0xbfb8aa3b, v100
	v_mul_f32_e32 v115, 0xbfb8aa3b, v101
	v_mul_f32_e32 v116, 0xbfb8aa3b, v102
	v_mul_f32_e32 v117, 0xbfb8aa3b, v103
	v_mul_f32_e32 v118, 0xbfb8aa3b, v104
	v_mul_f32_e32 v119, 0xbfb8aa3b, v105
	v_mul_f32_e32 v120, 0xbfb8aa3b, v106
	v_mul_f32_e32 v121, 0xbfb8aa3b, v107
	v_mul_f32_e32 v122, 0xbfb8aa3b, v108
	v_mul_f32_e32 v123, 0xbfb8aa3b, v109
	v_mul_f32_e32 v124, 0xbfb8aa3b, v110
	v_mul_f32_e32 v125, 0xbfb8aa3b, v111
	v_mul_f32_e32 v126, 0xbfb8aa3b, v112
	v_mul_f32_e32 v127, 0xbfb8aa3b, v113
	v_exp_f32_e32 v114, v114
	v_exp_f32_e32 v115, v115
	v_exp_f32_e32 v116, v116
	v_exp_f32_e32 v117, v117
	v_exp_f32_e32 v118, v118
	v_exp_f32_e32 v119, v119
	v_exp_f32_e32 v120, v120
	v_exp_f32_e32 v121, v121
	v_exp_f32_e32 v122, v122
	v_exp_f32_e32 v123, v123
	v_exp_f32_e32 v124, v124
	v_exp_f32_e32 v125, v125
	v_exp_f32_e32 v126, v126
	v_exp_f32_e32 v127, v127
	v_add_f32_e32 v114, 1.0, v114
	v_add_f32_e32 v115, 1.0, v115
	v_add_f32_e32 v116, 1.0, v116
	v_add_f32_e32 v117, 1.0, v117
	v_add_f32_e32 v118, 1.0, v118
	v_add_f32_e32 v119, 1.0, v119
	v_add_f32_e32 v120, 1.0, v120
	v_add_f32_e32 v121, 1.0, v121
	v_add_f32_e32 v122, 1.0, v122
	v_add_f32_e32 v123, 1.0, v123
	v_add_f32_e32 v124, 1.0, v124
	v_add_f32_e32 v125, 1.0, v125
	v_add_f32_e32 v126, 1.0, v126
	v_add_f32_e32 v127, 1.0, v127
	v_rcp_f32_e32 v114, v114
	v_rcp_f32_e32 v115, v115
	v_rcp_f32_e32 v116, v116
	v_rcp_f32_e32 v117, v117
	v_rcp_f32_e32 v118, v118
	v_rcp_f32_e32 v119, v119
	v_rcp_f32_e32 v120, v120
	v_rcp_f32_e32 v121, v121
	v_rcp_f32_e32 v122, v122
	v_rcp_f32_e32 v123, v123
	v_rcp_f32_e32 v124, v124
	v_rcp_f32_e32 v125, v125
	v_rcp_f32_e32 v126, v126
	v_rcp_f32_e32 v127, v127
	s_nop 0
	v_pk_mul_f32 v[100:101], v[100:101], v[114:115]
	v_pk_mul_f32 v[102:103], v[102:103], v[116:117]
	v_pk_mul_f32 v[104:105], v[104:105], v[118:119]
	v_pk_mul_f32 v[106:107], v[106:107], v[120:121]
	v_pk_mul_f32 v[108:109], v[108:109], v[122:123]
	v_pk_mul_f32 v[110:111], v[110:111], v[124:125]
	v_pk_mul_f32 v[112:113], v[112:113], v[126:127]
.Lconv_nosilu:
	v_mov_b64_e32 v[18:19], v[100:101]
	v_mov_b64_e32 v[12:13], v[102:103]
	v_mov_b64_e32 v[14:15], v[104:105]
	v_mov_b64_e32 v[28:29], v[106:107]
	v_mov_b64_e32 v[40:41], v[108:109]
	v_mov_b64_e32 v[42:43], v[110:111]
	v_mov_b64_e32 v[30:31], v[112:113]
